# up-projection epilogue: canonicalize and relu max fused into one v_max per element (issue slot kept as s_nop)
# speedup vs baseline: 1.0060x; 1.0045x over previous
; __device__ __forceinline__ unsigned cvt_pk_bf16(float lo, float hi) { unsigned r; asm volatile("v_cvt_pk_bf16_f32 %0, %1, %2" : "=v"(r) : "v"(lo), "v"(hi)); return r; }
;     __device__ __forceinline__ void operator()(const f32x4 (&acc)[2][2][4][2], const Unit& u, int wr, int wc, int fr, int fq) const {
;     ...
; #pragma unroll
;         for (int ai = 0; ai < 2; ++ai)
; #pragma unroll
;             for (int m = 0; m < 4; ++m) { const int row = row0 + ai * HALF + m * 16; bf16_t* rowp = O + (size_t)row * ldc + col0;
;                 const float rs = rsv[ai][m];
; #pragma unroll
;                 for (int bj = 0; bj < 2; ++bj) { f32x4 v0 = acc[ai][bj][m][0] * rs, v1 = acc[ai][bj][m][1] * rs;
;                     if (ACT == 1) {
; #pragma unroll
;                         for (int e = 0; e < 4; ++e) { float a = fmaxf(v0[e], 0.f), b = fmaxf(v1[e], 0.f); v0[e] = a * a; v1[e] = b * b; } }
;                     u32x4 o; o.x = cvt_pk_bf16(v0[0], v0[1]); o.y = cvt_pk_bf16(v0[2], v0[3]); o.z = cvt_pk_bf16(v1[0], v1[1]); o.w = cvt_pk_bf16(v1[2], v1[3]);
;                     *(u32x4*)(rowp + bj * HALF) = o; } }
.LBB0_1347:
	v_max_f32_e32 v122, 0, v122
	v_lshl_add_u32 v140, s48, 8, v142
	s_nop 0
	v_max_f32_e32 v123, 0, v123
	v_max_f32_e32 v124, 0, v124
	v_ashrrev_i32_e32 v141, 31, v140
	v_lshl_or_b32 v152, s56, 8, v144
	v_mul_f32_e32 v154, v122, v122
	v_max_f32_e32 v122, 0, v127
	s_nop 0
	s_nop 0
	v_or_b32_e32 v146, 16, v140
	v_or_b32_e32 v148, 32, v140
	v_or_b32_e32 v150, 48, v140
	v_ashrrev_i32_e32 v153, 31, v152
	v_lshlrev_b64 v[140:141], 14, v[140:141]
	v_max_f32_e32 v126, 0, v126
	s_nop 0
	v_mul_f32_e32 v127, v123, v123
	v_max_f32_e32 v123, 0, v128
	v_mul_f32_e32 v128, v124, v124
	v_max_f32_e32 v124, 0, v129
	v_max_f32_e32 v125, 0, v125
	v_lshl_add_u64 v[140:141], s[12:13], 0, v[140:141]
	v_lshlrev_b64 v[152:153], 1, v[152:153]
	s_nop 0
	v_mul_f32_e32 v122, v122, v122
	s_nop 0
	s_nop 0
	s_nop 0
	v_max_f32_e32 v114, 0, v114
	v_max_f32_e32 v115, 0, v115
	v_max_f32_e32 v116, 0, v116
	v_lshl_add_u64 v[140:141], v[140:141], 0, v[152:153]
	v_mul_f32_e32 v126, v126, v126
	v_mul_f32_e32 v123, v123, v123
	v_mul_f32_e32 v124, v124, v124
	v_mul_f32_e32 v125, v125, v125
	v_cvt_pk_bf16_f32 v122, v126, v122
	s_nop 0
	s_nop 0
	s_nop 0
	v_cvt_pk_bf16_f32 v123, v123, v124
	v_cvt_pk_bf16_f32 v124, v154, v127
	v_cvt_pk_bf16_f32 v125, v128, v125
	global_store_dwordx4 v[140:141], v[122:125], off
	v_max_f32_e32 v118, 0, v118
	v_max_f32_e32 v117, 0, v117
	v_mul_f32_e32 v122, v114, v114
	v_max_f32_e32 v114, 0, v119
	v_mul_f32_e32 v119, v115, v115
	v_max_f32_e32 v115, 0, v120
	v_mul_f32_e32 v120, v116, v116
	v_max_f32_e32 v116, 0, v121
	s_nop 0
	s_nop 0
	s_nop 0
	s_nop 0
	v_mul_f32_e32 v114, v114, v114
	v_mul_f32_e32 v115, v115, v115
	s_nop 0
	v_mul_f32_e32 v116, v116, v116
	v_max_f32_e32 v106, 0, v106
	v_mul_f32_e32 v118, v118, v118
	v_mul_f32_e32 v117, v117, v117
	v_cvt_pk_bf16_f32 v114, v118, v114
	v_cvt_pk_bf16_f32 v115, v115, v116
	v_cvt_pk_bf16_f32 v116, v122, v119
	s_nop 0
	v_max_f32_e32 v107, 0, v107
	v_max_f32_e32 v108, 0, v108
	v_ashrrev_i32_e32 v147, 31, v146
	v_cvt_pk_bf16_f32 v117, v120, v117
	global_store_dwordx4 v[140:141], v[114:117], off offset:256
	s_nop 0
	s_nop 0
	v_mul_f32_e32 v116, v106, v106
	v_max_f32_e32 v106, 0, v111
	v_lshlrev_b64 v[114:115], 14, v[146:147]
	v_max_f32_e32 v110, 0, v110
	s_nop 0
	v_mul_f32_e32 v111, v107, v107
	v_max_f32_e32 v107, 0, v112
	v_mul_f32_e32 v112, v108, v108
	v_max_f32_e32 v108, 0, v113
	v_max_f32_e32 v109, 0, v109
	v_lshl_add_u64 v[114:115], s[12:13], 0, v[114:115]
	s_nop 0
	v_mul_f32_e32 v106, v106, v106
	s_nop 0
	s_nop 0
	s_nop 0
	v_max_f32_e32 v98, 0, v98
	v_max_f32_e32 v99, 0, v99
	v_max_f32_e32 v100, 0, v100
	v_lshl_add_u64 v[114:115], v[114:115], 0, v[152:153]
	v_mul_f32_e32 v110, v110, v110
	v_mul_f32_e32 v107, v107, v107
	v_mul_f32_e32 v108, v108, v108
	v_mul_f32_e32 v109, v109, v109
	v_cvt_pk_bf16_f32 v106, v110, v106
	s_nop 0
	s_nop 0
	s_nop 0
	v_cvt_pk_bf16_f32 v107, v107, v108
	v_cvt_pk_bf16_f32 v108, v116, v111
	v_cvt_pk_bf16_f32 v109, v112, v109
	global_store_dwordx4 v[114:115], v[106:109], off
	v_max_f32_e32 v102, 0, v102
	v_max_f32_e32 v101, 0, v101
	v_mul_f32_e32 v106, v98, v98
	v_max_f32_e32 v98, 0, v103
	v_mul_f32_e32 v103, v99, v99
	v_max_f32_e32 v99, 0, v104
	v_mul_f32_e32 v104, v100, v100
	v_max_f32_e32 v100, 0, v105
	s_nop 0
	s_nop 0
	s_nop 0
	s_nop 0
	v_mul_f32_e32 v98, v98, v98
	v_mul_f32_e32 v99, v99, v99
	s_nop 0
	v_mul_f32_e32 v100, v100, v100
	v_max_f32_e32 v90, 0, v90
	v_mul_f32_e32 v102, v102, v102
	v_mul_f32_e32 v101, v101, v101
	v_cvt_pk_bf16_f32 v98, v102, v98
	v_cvt_pk_bf16_f32 v99, v99, v100
	v_cvt_pk_bf16_f32 v100, v106, v103
	s_nop 0
	v_max_f32_e32 v91, 0, v91
	v_max_f32_e32 v92, 0, v92
	v_ashrrev_i32_e32 v149, 31, v148
	v_cvt_pk_bf16_f32 v101, v104, v101
	global_store_dwordx4 v[114:115], v[98:101], off offset:256
	s_nop 0
	s_nop 0
	v_mul_f32_e32 v100, v90, v90
	v_max_f32_e32 v90, 0, v95
	v_lshlrev_b64 v[98:99], 14, v[148:149]
	v_max_f32_e32 v94, 0, v94
	s_nop 0
	v_mul_f32_e32 v95, v91, v91
	v_max_f32_e32 v91, 0, v96
	v_mul_f32_e32 v96, v92, v92
	v_max_f32_e32 v92, 0, v97
	v_max_f32_e32 v93, 0, v93
	v_lshl_add_u64 v[98:99], s[12:13], 0, v[98:99]
	s_nop 0
	v_mul_f32_e32 v90, v90, v90
	s_nop 0
	s_nop 0
	s_nop 0
	v_max_f32_e32 v82, 0, v82
	v_max_f32_e32 v83, 0, v83
	v_max_f32_e32 v84, 0, v84
	v_lshl_add_u64 v[98:99], v[98:99], 0, v[152:153]
	v_mul_f32_e32 v94, v94, v94
	v_mul_f32_e32 v91, v91, v91
	v_mul_f32_e32 v92, v92, v92
	v_mul_f32_e32 v93, v93, v93
	v_cvt_pk_bf16_f32 v90, v94, v90
	s_nop 0
	s_nop 0
	s_nop 0
	v_cvt_pk_bf16_f32 v91, v91, v92
	v_cvt_pk_bf16_f32 v92, v100, v95
	v_cvt_pk_bf16_f32 v93, v96, v93
	global_store_dwordx4 v[98:99], v[90:93], off
	v_max_f32_e32 v86, 0, v86
	v_max_f32_e32 v85, 0, v85
	v_mul_f32_e32 v90, v82, v82
	v_max_f32_e32 v82, 0, v87
	v_mul_f32_e32 v87, v83, v83
	v_max_f32_e32 v83, 0, v88
	v_mul_f32_e32 v88, v84, v84
	v_max_f32_e32 v84, 0, v89
	s_nop 0
	s_nop 0
	s_nop 0
	s_nop 0
	v_mul_f32_e32 v82, v82, v82
	v_mul_f32_e32 v83, v83, v83
	s_nop 0
	v_mul_f32_e32 v84, v84, v84
	v_max_f32_e32 v74, 0, v74
	v_mul_f32_e32 v86, v86, v86
	v_mul_f32_e32 v85, v85, v85
	v_cvt_pk_bf16_f32 v82, v86, v82
	v_cvt_pk_bf16_f32 v83, v83, v84
	v_cvt_pk_bf16_f32 v84, v90, v87
	s_nop 0
	v_max_f32_e32 v75, 0, v75
	v_max_f32_e32 v76, 0, v76
	v_ashrrev_i32_e32 v151, 31, v150
	v_cvt_pk_bf16_f32 v85, v88, v85
	global_store_dwordx4 v[98:99], v[82:85], off offset:256
	s_nop 0
	s_nop 0
	v_mul_f32_e32 v84, v74, v74
	v_max_f32_e32 v74, 0, v79
	v_lshlrev_b64 v[82:83], 14, v[150:151]
	v_max_f32_e32 v78, 0, v78
	s_nop 0
	v_mul_f32_e32 v79, v75, v75
	v_max_f32_e32 v75, 0, v80
	v_mul_f32_e32 v80, v76, v76
	v_max_f32_e32 v76, 0, v81
	v_max_f32_e32 v77, 0, v77
; __device__ __forceinline__ unsigned cvt_pk_bf16(float lo, float hi) { unsigned r; asm volatile("v_cvt_pk_bf16_f32 %0, %1, %2" : "=v"(r) : "v"(lo), "v"(hi)); return r; }
;     __device__ __forceinline__ void operator()(const f32x4 (&acc)[2][2][4][2], const Unit& u, int wr, int wc, int fr, int fq) const {
;     ...
; #pragma unroll
;         for (int ai = 0; ai < 2; ++ai)
; #pragma unroll
;             for (int m = 0; m < 4; ++m) { const int row = row0 + ai * HALF + m * 16; bf16_t* rowp = O + (size_t)row * ldc + col0;
;                 const float rs = rsv[ai][m];
; #pragma unroll
;                 for (int bj = 0; bj < 2; ++bj) { f32x4 v0 = acc[ai][bj][m][0] * rs, v1 = acc[ai][bj][m][1] * rs;
;                     if (ACT == 1) {
; #pragma unroll
;                         for (int e = 0; e < 4; ++e) { float a = fmaxf(v0[e], 0.f), b = fmaxf(v1[e], 0.f); v0[e] = a * a; v1[e] = b * b; } }
;                     u32x4 o; o.x = cvt_pk_bf16(v0[0], v0[1]); o.y = cvt_pk_bf16(v0[2], v0[3]); o.z = cvt_pk_bf16(v1[0], v1[1]); o.w = cvt_pk_bf16(v1[2], v1[3]);
;                     *(u32x4*)(rowp + bj * HALF) = o; } }
	v_lshl_add_u64 v[82:83], s[12:13], 0, v[82:83]
	s_nop 0
	v_mul_f32_e32 v74, v74, v74
	s_nop 0
	s_nop 0
	s_nop 0
	v_max_f32_e32 v66, 0, v66
	v_max_f32_e32 v67, 0, v67
	v_max_f32_e32 v68, 0, v68
	v_lshl_add_u64 v[82:83], v[82:83], 0, v[152:153]
	v_mul_f32_e32 v78, v78, v78
	v_mul_f32_e32 v75, v75, v75
	v_mul_f32_e32 v76, v76, v76
	v_mul_f32_e32 v77, v77, v77
	v_cvt_pk_bf16_f32 v74, v78, v74
	s_nop 0
	s_nop 0
	s_nop 0
	v_cvt_pk_bf16_f32 v75, v75, v76
	v_cvt_pk_bf16_f32 v76, v84, v79
	v_cvt_pk_bf16_f32 v77, v80, v77
	global_store_dwordx4 v[82:83], v[74:77], off
	v_max_f32_e32 v70, 0, v70
	v_max_f32_e32 v69, 0, v69
	v_mul_f32_e32 v74, v66, v66
	v_max_f32_e32 v66, 0, v71
	v_mul_f32_e32 v71, v67, v67
	v_max_f32_e32 v67, 0, v72
	v_mul_f32_e32 v72, v68, v68
	v_max_f32_e32 v68, 0, v73
	s_nop 0
	s_nop 0
	s_nop 0
	s_nop 0
	v_mul_f32_e32 v66, v66, v66
	v_mul_f32_e32 v67, v67, v67
	s_nop 0
	v_mul_f32_e32 v68, v68, v68
	v_max_f32_e32 v58, 0, v58
	v_mul_f32_e32 v70, v70, v70
	v_mul_f32_e32 v69, v69, v69
	v_cvt_pk_bf16_f32 v66, v70, v66
	v_cvt_pk_bf16_f32 v67, v67, v68
	v_cvt_pk_bf16_f32 v68, v74, v71
	s_nop 0
	v_max_f32_e32 v59, 0, v59
	v_max_f32_e32 v60, 0, v60
	v_cvt_pk_bf16_f32 v69, v72, v69
	global_store_dwordx4 v[82:83], v[66:69], off offset:256
	v_max_f32_e32 v62, 0, v62
	s_nop 0
	v_mul_f32_e32 v68, v58, v58
	v_max_f32_e32 v58, 0, v63
	s_nop 0
	s_mov_b64 s[2:3], 0x200000
	s_nop 0
	s_nop 0
	v_mul_f32_e32 v63, v59, v59
	v_max_f32_e32 v59, 0, v64
	v_mul_f32_e32 v64, v60, v60
	v_max_f32_e32 v60, 0, v65
	v_lshl_add_u64 v[66:67], v[140:141], 0, s[2:3]
	v_mul_f32_e32 v62, v62, v62
	v_mul_f32_e32 v58, v58, v58
	s_nop 0
	s_nop 0
	v_max_f32_e32 v61, 0, v61
	s_mov_b32 s2, 0x200000
	v_mul_f32_e32 v59, v59, v59
	s_nop 0
	v_mul_f32_e32 v60, v60, v60
	v_cvt_pk_bf16_f32 v58, v62, v58
	v_add_co_u32_e32 v62, vcc, s2, v140
	v_max_f32_e32 v50, 0, v50
	v_max_f32_e32 v51, 0, v51
	v_max_f32_e32 v52, 0, v52
	v_mul_f32_e32 v61, v61, v61
	v_cvt_pk_bf16_f32 v59, v59, v60
	v_cvt_pk_bf16_f32 v60, v68, v63
	v_addc_co_u32_e32 v63, vcc, 0, v141, vcc
	s_nop 0
	s_nop 0
	s_nop 0
	v_cvt_pk_bf16_f32 v61, v64, v61
	global_store_dwordx4 v[62:63], v[58:61], off
	v_max_f32_e32 v54, 0, v54
	v_max_f32_e32 v53, 0, v53
	v_mul_f32_e32 v58, v50, v50
	v_max_f32_e32 v50, 0, v55
	v_mul_f32_e32 v55, v51, v51
	v_max_f32_e32 v51, 0, v56
	v_mul_f32_e32 v56, v52, v52
	v_max_f32_e32 v52, 0, v57
	s_nop 0
	s_nop 0
	s_nop 0
	s_nop 0
	v_mul_f32_e32 v50, v50, v50
	v_mul_f32_e32 v51, v51, v51
	s_nop 0
	v_mul_f32_e32 v52, v52, v52
	v_max_f32_e32 v42, 0, v42
	v_mul_f32_e32 v54, v54, v54
	v_mul_f32_e32 v53, v53, v53
	v_cvt_pk_bf16_f32 v50, v54, v50
	v_cvt_pk_bf16_f32 v51, v51, v52
	v_cvt_pk_bf16_f32 v52, v58, v55
	s_nop 0
	v_max_f32_e32 v43, 0, v43
	v_max_f32_e32 v44, 0, v44
	v_cvt_pk_bf16_f32 v53, v56, v53
	global_store_dwordx4 v[66:67], v[50:53], off offset:256
	v_max_f32_e32 v46, 0, v46
	s_nop 0
	v_mul_f32_e32 v52, v42, v42
	v_max_f32_e32 v42, 0, v47
	s_nop 0
	s_mov_b64 s[2:3], 0x240000
	s_nop 0
	s_nop 0
	v_mul_f32_e32 v47, v43, v43
	v_max_f32_e32 v43, 0, v48
	v_mul_f32_e32 v48, v44, v44
	v_max_f32_e32 v44, 0, v49
	v_lshl_add_u64 v[50:51], v[140:141], 0, s[2:3]
	v_mul_f32_e32 v46, v46, v46
	v_mul_f32_e32 v42, v42, v42
	s_nop 0
	s_nop 0
	v_max_f32_e32 v45, 0, v45
	s_mov_b32 s2, 0x240000
	v_mul_f32_e32 v43, v43, v43
	s_nop 0
	v_mul_f32_e32 v44, v44, v44
	v_cvt_pk_bf16_f32 v42, v46, v42
	v_add_co_u32_e32 v46, vcc, s2, v140
	v_max_f32_e32 v34, 0, v34
	v_max_f32_e32 v35, 0, v35
	v_max_f32_e32 v36, 0, v36
	v_mul_f32_e32 v45, v45, v45
	v_cvt_pk_bf16_f32 v43, v43, v44
	v_cvt_pk_bf16_f32 v44, v52, v47
	v_addc_co_u32_e32 v47, vcc, 0, v141, vcc
	s_nop 0
	s_nop 0
	s_nop 0
	v_cvt_pk_bf16_f32 v45, v48, v45
	global_store_dwordx4 v[46:47], v[42:45], off
	v_max_f32_e32 v38, 0, v38
	v_max_f32_e32 v37, 0, v37
	v_mul_f32_e32 v42, v34, v34
; __device__ __forceinline__ unsigned cvt_pk_bf16(float lo, float hi) { unsigned r; asm volatile("v_cvt_pk_bf16_f32 %0, %1, %2" : "=v"(r) : "v"(lo), "v"(hi)); return r; }
;     __device__ __forceinline__ void operator()(const f32x4 (&acc)[2][2][4][2], const Unit& u, int wr, int wc, int fr, int fq) const {
;     ...
;                 for (int bj = 0; bj < 2; ++bj) { f32x4 v0 = acc[ai][bj][m][0] * rs, v1 = acc[ai][bj][m][1] * rs;
;                     if (ACT == 1) {
; #pragma unroll
;                         for (int e = 0; e < 4; ++e) { float a = fmaxf(v0[e], 0.f), b = fmaxf(v1[e], 0.f); v0[e] = a * a; v1[e] = b * b; } }
;                     u32x4 o; o.x = cvt_pk_bf16(v0[0], v0[1]); o.y = cvt_pk_bf16(v0[2], v0[3]); o.z = cvt_pk_bf16(v1[0], v1[1]); o.w = cvt_pk_bf16(v1[2], v1[3]);
;                     *(u32x4*)(rowp + bj * HALF) = o; } }
	v_max_f32_e32 v34, 0, v39
	v_mul_f32_e32 v39, v35, v35
	v_max_f32_e32 v35, 0, v40
	v_mul_f32_e32 v40, v36, v36
	v_max_f32_e32 v36, 0, v41
	s_nop 0
	s_nop 0
	s_nop 0
	s_nop 0
	v_mul_f32_e32 v34, v34, v34
	v_mul_f32_e32 v35, v35, v35
	s_nop 0
	v_mul_f32_e32 v36, v36, v36
	v_max_f32_e32 v26, 0, v26
	v_mul_f32_e32 v38, v38, v38
	v_mul_f32_e32 v37, v37, v37
	v_cvt_pk_bf16_f32 v34, v38, v34
	v_cvt_pk_bf16_f32 v35, v35, v36
	v_cvt_pk_bf16_f32 v36, v42, v39
	s_nop 0
	v_max_f32_e32 v27, 0, v27
	v_max_f32_e32 v28, 0, v28
	v_cvt_pk_bf16_f32 v37, v40, v37
	global_store_dwordx4 v[50:51], v[34:37], off offset:256
	v_max_f32_e32 v30, 0, v30
	s_nop 0
	v_mul_f32_e32 v36, v26, v26
	v_max_f32_e32 v26, 0, v31
	s_nop 0
	s_mov_b64 s[2:3], 0x280000
	s_nop 0
	s_nop 0
	v_mul_f32_e32 v31, v27, v27
	v_max_f32_e32 v27, 0, v32
	v_mul_f32_e32 v32, v28, v28
	v_max_f32_e32 v28, 0, v33
	v_lshl_add_u64 v[34:35], v[140:141], 0, s[2:3]
	v_mul_f32_e32 v30, v30, v30
	v_mul_f32_e32 v26, v26, v26
	s_nop 0
	s_nop 0
	v_max_f32_e32 v29, 0, v29
	s_mov_b32 s2, 0x280000
	v_mul_f32_e32 v27, v27, v27
	s_nop 0
	v_mul_f32_e32 v28, v28, v28
	v_cvt_pk_bf16_f32 v26, v30, v26
	v_add_co_u32_e32 v30, vcc, s2, v140
	v_max_f32_e32 v18, 0, v18
	v_max_f32_e32 v19, 0, v19
	v_max_f32_e32 v20, 0, v20
	v_mul_f32_e32 v29, v29, v29
	v_cvt_pk_bf16_f32 v27, v27, v28
	v_cvt_pk_bf16_f32 v28, v36, v31
	v_addc_co_u32_e32 v31, vcc, 0, v141, vcc
	s_nop 0
	s_nop 0
	s_nop 0
	v_cvt_pk_bf16_f32 v29, v32, v29
	global_store_dwordx4 v[30:31], v[26:29], off
	v_max_f32_e32 v22, 0, v22
	v_max_f32_e32 v21, 0, v21
	v_mul_f32_e32 v26, v18, v18
	v_max_f32_e32 v18, 0, v23
	v_mul_f32_e32 v23, v19, v19
	v_max_f32_e32 v19, 0, v24
	v_mul_f32_e32 v24, v20, v20
	v_max_f32_e32 v20, 0, v25
	s_nop 0
	s_nop 0
	s_nop 0
	s_nop 0
	v_mul_f32_e32 v18, v18, v18
	v_mul_f32_e32 v19, v19, v19
	s_nop 0
	v_mul_f32_e32 v20, v20, v20
	v_max_f32_e32 v10, 0, v10
	v_mul_f32_e32 v22, v22, v22
	v_mul_f32_e32 v21, v21, v21
	v_cvt_pk_bf16_f32 v18, v22, v18
	v_cvt_pk_bf16_f32 v19, v19, v20
	v_cvt_pk_bf16_f32 v20, v26, v23
	s_nop 0
	v_max_f32_e32 v11, 0, v11
	v_max_f32_e32 v12, 0, v12
	v_cvt_pk_bf16_f32 v21, v24, v21
	global_store_dwordx4 v[34:35], v[18:21], off offset:256
	v_max_f32_e32 v14, 0, v14
	s_nop 0
	v_mul_f32_e32 v20, v10, v10
	v_max_f32_e32 v10, 0, v15
	s_nop 0
	s_mov_b64 s[2:3], 0x2c0000
	s_nop 0
	s_nop 0
	v_mul_f32_e32 v15, v11, v11
	v_max_f32_e32 v11, 0, v16
	v_mul_f32_e32 v16, v12, v12
	v_max_f32_e32 v12, 0, v17
	v_lshl_add_u64 v[18:19], v[140:141], 0, s[2:3]
	v_mul_f32_e32 v14, v14, v14
	v_mul_f32_e32 v10, v10, v10
	s_nop 0
	s_nop 0
	v_max_f32_e32 v13, 0, v13
	s_mov_b32 s2, 0x2c0000
	v_mul_f32_e32 v11, v11, v11
	s_nop 0
	v_mul_f32_e32 v12, v12, v12
	v_cvt_pk_bf16_f32 v10, v14, v10
	v_add_co_u32_e32 v14, vcc, s2, v140
	v_max_f32_e32 v2, 0, v2
	v_max_f32_e32 v3, 0, v3
	v_max_f32_e32 v4, 0, v4
	v_mul_f32_e32 v13, v13, v13
	v_cvt_pk_bf16_f32 v11, v11, v12
	v_cvt_pk_bf16_f32 v12, v20, v15
	v_addc_co_u32_e32 v15, vcc, 0, v141, vcc
	s_nop 0
	s_nop 0
	s_nop 0
	v_cvt_pk_bf16_f32 v13, v16, v13
	global_store_dwordx4 v[14:15], v[10:13], off
	v_max_f32_e32 v5, 0, v5
	v_max_f32_e32 v6, 0, v6
	v_mul_f32_e32 v10, v2, v2
	v_max_f32_e32 v2, 0, v7
	v_mul_f32_e32 v7, v3, v3
	v_max_f32_e32 v3, 0, v8
	v_mul_f32_e32 v8, v4, v4
	v_max_f32_e32 v4, 0, v9
	s_nop 0
	s_nop 0
	s_nop 0
	s_nop 0
	s_nop 0
	v_mul_f32_e32 v2, v2, v2
	v_mul_f32_e32 v3, v3, v3
	v_mul_f32_e32 v4, v4, v4
	v_mul_f32_e32 v5, v5, v5
	s_andn2_b64 vcc, exec, s[38:39]
	s_mov_b64 s[2:3], -1
	v_mul_f32_e32 v6, v6, v6
	v_cvt_pk_bf16_f32 v2, v6, v2
	v_cvt_pk_bf16_f32 v3, v3, v4
	v_cvt_pk_bf16_f32 v4, v10, v7
	v_cvt_pk_bf16_f32 v5, v8, v5
	global_store_dwordx4 v[18:19], v[2:5], off offset:256
	s_cbranch_vccnz .LBB0_1336
	s_andn2_b64 vcc, exec, s[8:9]
	s_cbranch_vccnz .LBB0_1335
	s_barrier
	s_branch .LBB0_1335
